# phase 3 chunk_prep: q/k tile staging loads issued four groups at a time into otherwise unused registers (were eight serialized load-wait-convert groups)
# baseline (speedup 1.0000x reference)
; DI void chunk_prep(const Params& p, int item, char* smem) {
;     ...
; #pragma unroll
;   for (int i = 0; i < 8; ++i) {
;     int idx = tid + i * 256, row = idx >> 5, c4 = idx & 31;
;     float4 q = *(const float4*)(p.QKV + (row0 + row) * 1536 + hh * 128 + c4 * 4);
;     float4 k = *(const float4*)(p.QKV + (row0 + row) * 1536 + 512 + hh * 128 + c4 * 4);
;     uint2 qo, ko;
;     qo.x = pack2(q.x, q.y); qo.y = pack2(q.z, q.w);
;     ko.x = pack2(k.x, k.y); ko.y = pack2(k.z, k.w);
;     *(uint2*)(qs + row * 136 + c4 * 4) = qo;
;     *(uint2*)(ks_ + row * 136 + c4 * 4) = ko;
;   }
.LBB0_376:
	s_or_b64 exec, exec, s[50:51]
	v_or_b32_e32 v0, s48, v34
	v_mov_b64_e32 v[8:9], s[44:45]
	s_mul_i32 s53, s49, 0x1800
	v_mad_u64_u32 v[0:1], s[50:51], v0, s52, v[8:9]
	v_add_u32_e32 v1, s53, v1
	s_lshl_b32 s30, s54, 2
	v_lshl_add_u64 v[0:1], v[0:1], 0, s[30:31]
	v_lshl_add_u64 v[4:5], v[0:1], 0, v[32:33]
	global_load_dwordx4 v[216:219], v[4:5], off
	global_load_dwordx4 v[220:223], v[4:5], off offset:2048
	v_mov_b32_e32 v77, 0
	v_mov_b32_e32 v79, 0
	v_or_b32_e32 v0, s48, v36
	v_mad_u64_u32 v[0:1], s[50:51], v0, s52, v[8:9]
	v_add_u32_e32 v1, s53, v1
	v_lshl_add_u64 v[0:1], v[0:1], 0, s[30:31]
	v_lshl_add_u64 v[4:5], v[0:1], 0, v[32:33]
	global_load_dwordx4 v[224:227], v[4:5], off
	global_load_dwordx4 v[228:231], v[4:5], off offset:2048
	v_or_b32_e32 v0, s48, v38
	v_mad_u64_u32 v[0:1], s[50:51], v0, s52, v[8:9]
	v_add_u32_e32 v1, s53, v1
	v_lshl_add_u64 v[0:1], v[0:1], 0, s[30:31]
	v_lshl_add_u64 v[4:5], v[0:1], 0, v[32:33]
	global_load_dwordx4 v[232:235], v[4:5], off
	global_load_dwordx4 v[236:239], v[4:5], off offset:2048
	v_or_b32_e32 v0, s48, v40
	v_mad_u64_u32 v[0:1], s[50:51], v0, s52, v[8:9]
	v_add_u32_e32 v1, s53, v1
	v_lshl_add_u64 v[0:1], v[0:1], 0, s[30:31]
	v_lshl_add_u64 v[4:5], v[0:1], 0, v[32:33]
	global_load_dwordx4 v[240:243], v[4:5], off
	global_load_dwordx4 v[244:247], v[4:5], off offset:2048
	s_waitcnt vmcnt(7)
	v_cvt_pk_bf16_f32 v0, v216, v217
	v_cvt_pk_bf16_f32 v1, v218, v219
	s_waitcnt vmcnt(6)
	v_cvt_pk_bf16_f32 v2, v220, v221
	v_cvt_pk_bf16_f32 v3, v222, v223
	ds_write2st64_b64 v39, v[0:1], v[2:3] offset0:2 offset1:36
	s_waitcnt vmcnt(5)
	v_cvt_pk_bf16_f32 v0, v224, v225
	v_cvt_pk_bf16_f32 v1, v226, v227
	s_waitcnt vmcnt(4)
	v_cvt_pk_bf16_f32 v2, v228, v229
	v_cvt_pk_bf16_f32 v3, v230, v231
	ds_write2st64_b64 v41, v[0:1], v[2:3] offset0:2 offset1:36
	s_waitcnt vmcnt(3)
	v_cvt_pk_bf16_f32 v0, v232, v233
	v_cvt_pk_bf16_f32 v1, v234, v235
	s_waitcnt vmcnt(2)
	v_cvt_pk_bf16_f32 v2, v236, v237
	v_cvt_pk_bf16_f32 v3, v238, v239
	ds_write2st64_b64 v43, v[0:1], v[2:3] offset0:2 offset1:36
	s_waitcnt vmcnt(1)
	v_cvt_pk_bf16_f32 v0, v240, v241
	v_cvt_pk_bf16_f32 v1, v242, v243
	s_waitcnt vmcnt(0)
	v_cvt_pk_bf16_f32 v2, v244, v245
	v_cvt_pk_bf16_f32 v3, v246, v247
	ds_write2st64_b64 v51, v[0:1], v[2:3] offset0:2 offset1:36
	v_or_b32_e32 v0, s48, v42
	v_mad_u64_u32 v[0:1], s[50:51], v0, s52, v[8:9]
	v_add_u32_e32 v1, s53, v1
	v_lshl_add_u64 v[0:1], v[0:1], 0, s[30:31]
	v_lshl_add_u64 v[4:5], v[0:1], 0, v[32:33]
	global_load_dwordx4 v[216:219], v[4:5], off
	global_load_dwordx4 v[220:223], v[4:5], off offset:2048
	v_lshl_add_u64 v[0:1], s[48:49], 0, v[44:45]
	v_mad_u64_u32 v[2:3], s[50:51], v0, s52, v[8:9]
	v_mov_b32_e32 v0, v3
	v_mad_u64_u32 v[0:1], s[50:51], v1, s52, v[0:1]
	v_mov_b32_e32 v3, v0
	v_lshl_add_u64 v[0:1], v[2:3], 0, s[30:31]
	v_lshl_add_u64 v[4:5], v[0:1], 0, v[32:33]
	global_load_dwordx4 v[224:227], v[4:5], off
	global_load_dwordx4 v[228:231], v[4:5], off offset:2048
	v_lshl_add_u64 v[0:1], s[48:49], 0, v[46:47]
	v_mad_u64_u32 v[2:3], s[50:51], v0, s52, v[8:9]
	v_mov_b32_e32 v0, v3
	v_mad_u64_u32 v[0:1], s[50:51], v1, s52, v[0:1]
	v_mov_b32_e32 v3, v0
	v_lshl_add_u64 v[0:1], v[2:3], 0, s[30:31]
	v_lshl_add_u64 v[4:5], v[0:1], 0, v[32:33]
	global_load_dwordx4 v[232:235], v[4:5], off
	global_load_dwordx4 v[236:239], v[4:5], off offset:2048
	v_lshl_add_u64 v[0:1], s[48:49], 0, v[48:49]
	v_mad_u64_u32 v[2:3], s[50:51], v0, s52, v[8:9]
	v_mov_b32_e32 v0, v3
	v_mad_u64_u32 v[0:1], s[50:51], v1, s52, v[0:1]
	v_mov_b32_e32 v3, v0
	v_lshl_add_u64 v[0:1], v[2:3], 0, s[30:31]
	v_lshl_add_u64 v[4:5], v[0:1], 0, v[32:33]
	global_load_dwordx4 v[240:243], v[4:5], off
	global_load_dwordx4 v[244:247], v[4:5], off offset:2048
	s_waitcnt vmcnt(7)
	v_cvt_pk_bf16_f32 v0, v216, v217
	v_cvt_pk_bf16_f32 v1, v218, v219
	s_waitcnt vmcnt(6)
	v_cvt_pk_bf16_f32 v2, v220, v221
	v_cvt_pk_bf16_f32 v3, v222, v223
	ds_write2st64_b64 v59, v[0:1], v[2:3] offset0:2 offset1:36
	s_waitcnt vmcnt(5)
	v_cvt_pk_bf16_f32 v0, v224, v225
	v_cvt_pk_bf16_f32 v1, v226, v227
	s_waitcnt vmcnt(4)
	v_cvt_pk_bf16_f32 v2, v228, v229
	v_cvt_pk_bf16_f32 v3, v230, v231
	ds_write2st64_b64 v61, v[0:1], v[2:3] offset0:2 offset1:36
	s_waitcnt vmcnt(3)
	v_cvt_pk_bf16_f32 v0, v232, v233
	v_cvt_pk_bf16_f32 v1, v234, v235
	s_waitcnt vmcnt(2)
	v_cvt_pk_bf16_f32 v2, v236, v237
	v_cvt_pk_bf16_f32 v3, v238, v239
	ds_write2st64_b64 v63, v[0:1], v[2:3] offset0:2 offset1:36
	s_waitcnt vmcnt(1)
	v_cvt_pk_bf16_f32 v0, v240, v241
	v_cvt_pk_bf16_f32 v1, v242, v243
	s_waitcnt vmcnt(0)
	v_cvt_pk_bf16_f32 v2, v244, v245
	v_cvt_pk_bf16_f32 v3, v246, v247
	ds_write2st64_b64 v65, v[0:1], v[2:3] offset0:2 offset1:36
	s_waitcnt lgkmcnt(0)
	s_barrier
; #define MFMA32(a, b, c) __builtin_amdgcn_mfma_f32_32x32x16_bf16((a), (b), (c), 0, 0, 0)
; DI int crow(int reg, int h) { return (reg & 3) + 8 * (reg >> 2) + 4 * h; }
; DI void chunk_prep(const Params& p, int item, char* smem) {
;     ...
;   {
;     const int mi = wid >> 1, ni = wid & 1;
;     f32x16 akk, aqk;
; #pragma unroll
;     for (int q = 0; q < 16; ++q) { akk[q] = 0.f; aqk[q] = 0.f; }
; #pragma unroll
;     for (int ks = 0; ks < 8; ++ks) {
;       bf16x8 ka = *(const bf16x8*)(ks_ + (mi * 32 + r) * 136 + ks * 16 + hl * 8);
;       bf16x8 qa = *(const bf16x8*)(qs + (mi * 32 + r) * 136 + ks * 16 + hl * 8);
;       bf16x8 kb = *(const bf16x8*)(ks_ + (ni * 32 + r) * 136 + ks * 16 + hl * 8);
;       akk = MFMA32(ka, kb, akk);
;       aqk = MFMA32(qa, kb, aqk);
;     }
;     bfr* qkf = (bfr*)(p.QKF + (size_t)item * 512);
; #pragma unroll
;     for (int q = 0; q < 16; ++q) {
;       int i = mi * 32 + crow(q, hl), j = ni * 32 + r;
;       float dec = (i >= j) ? __expf(gcs[i] - gcs[j]) : 0.f;
;       Am[i * 68 + j] = (i > j) ? akk[q] * betas[i] * dec : 0.f;
	ds_read_b128 v[0:3], v67 offset:18432
	ds_read_b128 v[4:7], v69 offset:18432
	ds_read_b128 v[90:93], v69 offset:18464
	s_waitcnt lgkmcnt(1)
	v_mfma_f32_32x32x16_bf16 v[16:31], v[0:3], v[4:7], 0
	ds_read_b128 v[0:3], v67 offset:1024
	ds_read_b128 v[208:211], v67 offset:1056
	ds_read_b128 v[212:215], v67 offset:18464
	s_waitcnt lgkmcnt(2)
	v_mfma_f32_32x32x16_bf16 v[0:15], v[0:3], v[4:7], 0
	s_waitcnt lgkmcnt(0)
	v_mfma_f32_32x32x16_bf16 v[16:31], v[212:215], v[90:93], v[16:31]
	v_mfma_f32_32x32x16_bf16 v[0:15], v[208:211], v[90:93], v[0:15]
	ds_read_b128 v[90:93], v67 offset:18496
	ds_read_b128 v[208:211], v67 offset:1088
	ds_read_b128 v[212:215], v69 offset:18496
	s_waitcnt lgkmcnt(0)
	v_mfma_f32_32x32x16_bf16 v[16:31], v[90:93], v[212:215], v[16:31]
	v_mfma_f32_32x32x16_bf16 v[0:15], v[208:211], v[212:215], v[0:15]
	ds_read_b128 v[90:93], v67 offset:18528
	ds_read_b128 v[208:211], v67 offset:1120
	ds_read_b128 v[212:215], v69 offset:18528
	s_waitcnt lgkmcnt(0)
	v_mfma_f32_32x32x16_bf16 v[16:31], v[90:93], v[212:215], v[16:31]
	v_mfma_f32_32x32x16_bf16 v[0:15], v[208:211], v[212:215], v[0:15]
	ds_read_b128 v[90:93], v67 offset:18560
	ds_read_b128 v[208:211], v67 offset:1152
	ds_read_b128 v[212:215], v69 offset:18560
	s_waitcnt lgkmcnt(0)
	v_mfma_f32_32x32x16_bf16 v[16:31], v[90:93], v[212:215], v[16:31]
	v_mfma_f32_32x32x16_bf16 v[0:15], v[208:211], v[212:215], v[0:15]
	ds_read_b128 v[90:93], v67 offset:18592
	ds_read_b128 v[208:211], v67 offset:1184
	ds_read_b128 v[212:215], v69 offset:18592
	s_waitcnt lgkmcnt(0)
	v_mfma_f32_32x32x16_bf16 v[16:31], v[90:93], v[212:215], v[16:31]
	v_mfma_f32_32x32x16_bf16 v[0:15], v[208:211], v[212:215], v[0:15]
	ds_read_b128 v[90:93], v67 offset:18624
	ds_read_b128 v[208:211], v67 offset:1216
	ds_read_b128 v[212:215], v69 offset:18624
	s_waitcnt lgkmcnt(0)
	v_mfma_f32_32x32x16_bf16 v[16:31], v[90:93], v[212:215], v[16:31]
	v_mfma_f32_32x32x16_bf16 v[0:15], v[208:211], v[212:215], v[0:15]
	ds_read_b128 v[90:93], v67 offset:18656
	ds_read_b128 v[208:211], v67 offset:1248
	ds_read_b128 v[212:215], v69 offset:18656
	s_waitcnt lgkmcnt(0)
	v_mfma_f32_32x32x16_bf16 v[16:31], v[90:93], v[212:215], v[16:31]
	v_mfma_f32_32x32x16_bf16 v[0:15], v[208:211], v[212:215], v[0:15]
	s_and_saveexec_b64 s[50:51], s[62:63]
	s_cbranch_execz .LBB0_378
	ds_read_b32 v79, v73
	ds_read_b32 v81, v71
	s_waitcnt lgkmcnt(0)
	v_sub_f32_e32 v79, v79, v81
	v_mul_f32_e32 v79, 0x3fb8aa3b, v79
	v_exp_f32_e32 v79, v79
